# PRO phase: adaLN GEMV loop issues its 16 weight loads per iteration up front (was 4 per wait); QKV/pool weight transposes issue all 32 loads before one wait (was 2 per wait)
# speedup vs baseline: 1.0177x; 1.0177x over previous
.LBB0_1022:
	v_add_co_u32_e32 v116, vcc, 0xfff4c000, v20
	s_nop 1
	v_addc_co_u32_e32 v117, vcc, -1, v21, vcc
	global_load_dword v100, v[116:117], off
	v_add_co_u32_e32 v116, vcc, 0xfff58000, v20
	s_nop 1
	v_addc_co_u32_e32 v117, vcc, -1, v21, vcc
	global_load_dword v101, v[116:117], off
	v_add_co_u32_e32 v116, vcc, 0xfff64000, v20
	s_nop 1
	v_addc_co_u32_e32 v117, vcc, -1, v21, vcc
	global_load_dword v102, v[116:117], off
	v_add_co_u32_e32 v116, vcc, 0xfff70000, v20
	s_nop 1
	v_addc_co_u32_e32 v117, vcc, -1, v21, vcc
	global_load_dword v103, v[116:117], off
	v_add_co_u32_e32 v116, vcc, 0xfff7c000, v20
	s_nop 1
	v_addc_co_u32_e32 v117, vcc, -1, v21, vcc
	global_load_dword v104, v[116:117], off
	v_add_co_u32_e32 v116, vcc, 0xfff88000, v20
	s_nop 1
	v_addc_co_u32_e32 v117, vcc, -1, v21, vcc
	global_load_dword v105, v[116:117], off
	v_add_co_u32_e32 v116, vcc, 0xfff94000, v20
	s_nop 1
	v_addc_co_u32_e32 v117, vcc, -1, v21, vcc
	global_load_dword v106, v[116:117], off
	v_add_co_u32_e32 v116, vcc, 0xfffa0000, v20
	s_nop 1
	v_addc_co_u32_e32 v117, vcc, -1, v21, vcc
	global_load_dword v107, v[116:117], off
	v_add_co_u32_e32 v116, vcc, 0xfffac000, v20
	s_nop 1
	v_addc_co_u32_e32 v117, vcc, -1, v21, vcc
	global_load_dword v108, v[116:117], off
	v_add_co_u32_e32 v116, vcc, 0xfffb8000, v20
	s_nop 1
	v_addc_co_u32_e32 v117, vcc, -1, v21, vcc
	global_load_dword v109, v[116:117], off
	v_add_co_u32_e32 v116, vcc, 0xfffc4000, v20
	s_nop 1
	v_addc_co_u32_e32 v117, vcc, -1, v21, vcc
	global_load_dword v110, v[116:117], off
	v_add_co_u32_e32 v116, vcc, 0xfffd0000, v20
	s_nop 1
	v_addc_co_u32_e32 v117, vcc, -1, v21, vcc
	global_load_dword v111, v[116:117], off
	v_add_co_u32_e32 v116, vcc, 0xfffdc000, v20
	s_nop 1
	v_addc_co_u32_e32 v117, vcc, -1, v21, vcc
	global_load_dword v112, v[116:117], off
	v_add_co_u32_e32 v116, vcc, 0xfffe8000, v20
	s_nop 1
	v_addc_co_u32_e32 v117, vcc, -1, v21, vcc
	global_load_dword v113, v[116:117], off
	v_add_co_u32_e32 v116, vcc, 0xffff4000, v20
	s_nop 1
	v_addc_co_u32_e32 v117, vcc, -1, v21, vcc
	global_load_dword v114, v[116:117], off
	global_load_dword v115, v[20:21], off
	v_add_co_u32_e32 v2, vcc, 0xfff4c000, v20
	s_mov_b32 s23, 0xfff7c000
	s_nop 0
	v_addc_co_u32_e32 v3, vcc, -1, v21, vcc
	s_waitcnt vmcnt(12)
	v_mov_b32_e32 v48, v100
	v_add_co_u32_e32 v2, vcc, 0xfff58000, v20
	s_add_i32 s22, s22, 16
	s_nop 0
	v_addc_co_u32_e32 v3, vcc, -1, v21, vcc
	v_mov_b32_e32 v50, v101
	v_add_co_u32_e32 v2, vcc, 0xfff64000, v20
	s_mov_b64 s[26:27], 0xc0000
	s_nop 0
	v_addc_co_u32_e32 v3, vcc, -1, v21, vcc
	v_mov_b32_e32 v34, v102
	v_add_co_u32_e32 v2, vcc, 0xfff70000, v20
	s_cmp_gt_u32 s22, 59
	s_nop 0
	v_addc_co_u32_e32 v3, vcc, -1, v21, vcc
	v_mov_b32_e32 v52, v103
	ds_read_b128 v[30:33], v38
	ds_read_b128 v[10:13], v38 offset:16
	ds_read_b128 v[6:9], v38 offset:32
	ds_read_b128 v[2:5], v38 offset:48
	ds_read_b128 v[40:43], v38 offset:2048
	s_waitcnt lgkmcnt(4)
	v_mov_b32_e32 v44, v30
	s_waitcnt lgkmcnt(0)
	v_mov_b32_e32 v45, v40
	v_mov_b32_e32 v40, v31
	v_pk_mul_f32 v[30:31], v[50:51], v[40:41] op_sel_hi:[0,1]
	v_mov_b32_e32 v41, v42
	v_mov_b32_e32 v42, v33
	v_mov_b32_e32 v40, v32
	v_pk_fma_f32 v[30:31], v[48:49], v[44:45], v[30:31] op_sel_hi:[0,1,1]
	v_pk_mul_f32 v[32:33], v[52:53], v[42:43] op_sel_hi:[0,1]
	v_pk_fma_f32 v[32:33], v[34:35], v[40:41], v[32:33] op_sel_hi:[0,1,1]
	ds_read_b128 v[40:43], v38 offset:4096
	ds_read_b128 v[44:47], v38 offset:6144
	v_pk_add_f32 v[30:31], v[30:31], v[32:33]
	s_nop 0
	v_pk_add_f32 v[32:33], v[22:23], v[30:31]
	s_waitcnt lgkmcnt(1)
	v_mov_b32_e32 v22, v40
	s_waitcnt lgkmcnt(0)
	v_mov_b32_e32 v23, v44
	v_mov_b32_e32 v44, v41
	v_pk_mul_f32 v[30:31], v[50:51], v[44:45] op_sel_hi:[0,1]
	v_pk_fma_f32 v[22:23], v[48:49], v[22:23], v[30:31] op_sel_hi:[0,1,1]
	v_mov_b32_e32 v31, v46
	v_mov_b32_e32 v46, v43
	v_mov_b32_e32 v30, v42
	v_pk_mul_f32 v[40:41], v[52:53], v[46:47] op_sel_hi:[0,1]
	v_pk_fma_f32 v[30:31], v[34:35], v[30:31], v[40:41] op_sel_hi:[0,1,1]
	v_pk_add_f32 v[22:23], v[22:23], v[30:31]
	s_nop 0
	v_pk_add_f32 v[30:31], v[24:25], v[22:23]
	ds_read_b128 v[22:25], v38 offset:8192
	ds_read_b128 v[40:43], v38 offset:10240
	s_waitcnt lgkmcnt(1)
	v_mov_b32_e32 v44, v22
	s_waitcnt lgkmcnt(0)
	v_mov_b32_e32 v45, v40
	v_mov_b32_e32 v40, v23
	v_pk_mul_f32 v[22:23], v[50:51], v[40:41] op_sel_hi:[0,1]
	v_mov_b32_e32 v41, v42
	v_mov_b32_e32 v42, v25
	v_mov_b32_e32 v40, v24
	v_pk_mul_f32 v[24:25], v[52:53], v[42:43] op_sel_hi:[0,1]
	v_pk_fma_f32 v[22:23], v[48:49], v[44:45], v[22:23] op_sel_hi:[0,1,1]
	v_pk_fma_f32 v[24:25], v[34:35], v[40:41], v[24:25] op_sel_hi:[0,1,1]
	v_pk_add_f32 v[22:23], v[22:23], v[24:25]
	s_nop 0
	v_pk_add_f32 v[26:27], v[26:27], v[22:23]
	ds_read_b128 v[22:25], v38 offset:12288
	ds_read_b128 v[40:43], v38 offset:14336
	s_waitcnt lgkmcnt(1)
	v_mov_b32_e32 v44, v22
	s_waitcnt lgkmcnt(0)
	v_mov_b32_e32 v45, v40
	v_mov_b32_e32 v40, v23
	v_pk_mul_f32 v[22:23], v[50:51], v[40:41] op_sel_hi:[0,1]
	v_mov_b32_e32 v41, v42
	v_mov_b32_e32 v42, v25
	v_mov_b32_e32 v40, v24
	v_pk_mul_f32 v[24:25], v[52:53], v[42:43] op_sel_hi:[0,1]
	v_pk_fma_f32 v[24:25], v[34:35], v[40:41], v[24:25] op_sel_hi:[0,1,1]
	ds_read_b128 v[40:43], v38 offset:16384
	v_pk_fma_f32 v[22:23], v[48:49], v[44:45], v[22:23] op_sel_hi:[0,1,1]
	v_pk_add_f32 v[22:23], v[22:23], v[24:25]
	v_mov_b32_e32 v49, v52
	v_pk_add_f32 v[22:23], v[28:29], v[22:23]
	s_waitcnt lgkmcnt(0)
	v_mov_b32_e32 v24, v41
	v_mov_b32_e32 v41, v43
	v_mov_b32_e32 v51, v34
	v_mov_b32_e32 v25, v42
	v_pk_mul_f32 v[28:29], v[48:49], v[40:41]
	v_mov_b32_e32 v44, v10
	v_pk_fma_f32 v[24:25], v[50:51], v[24:25], v[28:29]
	s_nop 0
	v_add_f32_e32 v24, v24, v25
	v_add_f32_e32 v39, v0, v24
	v_add_co_u32_e32 v24, vcc, s23, v20
	s_mov_b32 s23, 0xfff88000
	s_nop 0
	v_addc_co_u32_e32 v25, vcc, -1, v21, vcc
	v_add_co_u32_e32 v28, vcc, s23, v20
	s_mov_b32 s23, 0xfff94000
	s_nop 0
	v_addc_co_u32_e32 v29, vcc, -1, v21, vcc
	v_add_co_u32_e32 v40, vcc, s23, v20
	s_mov_b32 s23, 0xfffa0000
	s_nop 0
	v_addc_co_u32_e32 v41, vcc, -1, v21, vcc
	s_waitcnt vmcnt(8)
	v_mov_b32_e32 v24, v104
	s_nop 0
	v_mov_b32_e32 v28, v105
	s_nop 0
	v_mov_b32_e32 v0, v106
	v_add_co_u32_e32 v40, vcc, s23, v20
	s_mov_b32 s23, 0xfffac000
	s_nop 0
	v_addc_co_u32_e32 v41, vcc, -1, v21, vcc
	v_mov_b32_e32 v34, v107
	ds_read_b128 v[40:43], v38 offset:2064
	s_waitcnt lgkmcnt(0)
	v_mov_b32_e32 v45, v40
	v_mov_b32_e32 v40, v11
	v_pk_mul_f32 v[10:11], v[28:29], v[40:41] op_sel_hi:[0,1]
	v_mov_b32_e32 v41, v42
	v_mov_b32_e32 v42, v13
	v_mov_b32_e32 v40, v12
	v_pk_fma_f32 v[10:11], v[24:25], v[44:45], v[10:11] op_sel_hi:[0,1,1]
	v_pk_mul_f32 v[12:13], v[34:35], v[42:43] op_sel_hi:[0,1]
	v_pk_fma_f32 v[12:13], v[0:1], v[40:41], v[12:13] op_sel_hi:[0,1,1]
	ds_read_b128 v[40:43], v38 offset:4112
	ds_read_b128 v[44:47], v38 offset:6160
	v_pk_add_f32 v[10:11], v[10:11], v[12:13]
	s_waitcnt lgkmcnt(1)
	v_mov_b32_e32 v12, v40
	s_waitcnt lgkmcnt(0)
	v_mov_b32_e32 v13, v44
	v_mov_b32_e32 v44, v41
	v_pk_add_f32 v[10:11], v[32:33], v[10:11]
	v_pk_mul_f32 v[32:33], v[28:29], v[44:45] op_sel_hi:[0,1]
	v_pk_fma_f32 v[12:13], v[24:25], v[12:13], v[32:33] op_sel_hi:[0,1,1]
	v_mov_b32_e32 v33, v46
	v_mov_b32_e32 v46, v43
	v_mov_b32_e32 v32, v42
	v_pk_mul_f32 v[40:41], v[34:35], v[46:47] op_sel_hi:[0,1]
	v_pk_fma_f32 v[32:33], v[0:1], v[32:33], v[40:41] op_sel_hi:[0,1,1]
	v_pk_add_f32 v[12:13], v[12:13], v[32:33]
	s_nop 0
	v_pk_add_f32 v[12:13], v[30:31], v[12:13]
	ds_read_b128 v[30:33], v38 offset:8208
	ds_read_b128 v[40:43], v38 offset:10256
	s_waitcnt lgkmcnt(1)
	v_mov_b32_e32 v44, v30
	s_waitcnt lgkmcnt(0)
	v_mov_b32_e32 v45, v40
	v_mov_b32_e32 v40, v31
	v_pk_mul_f32 v[30:31], v[28:29], v[40:41] op_sel_hi:[0,1]
	v_mov_b32_e32 v41, v42
	v_mov_b32_e32 v42, v33
	v_mov_b32_e32 v40, v32
	v_pk_mul_f32 v[32:33], v[34:35], v[42:43] op_sel_hi:[0,1]
	v_pk_fma_f32 v[30:31], v[24:25], v[44:45], v[30:31] op_sel_hi:[0,1,1]
	v_pk_fma_f32 v[32:33], v[0:1], v[40:41], v[32:33] op_sel_hi:[0,1,1]
	v_pk_add_f32 v[30:31], v[30:31], v[32:33]
	s_nop 0
	v_pk_add_f32 v[44:45], v[26:27], v[30:31]
	ds_read_b128 v[30:33], v38 offset:12304
	ds_read_b128 v[40:43], v38 offset:14352
	s_waitcnt lgkmcnt(1)
	v_mov_b32_e32 v26, v30
	s_waitcnt lgkmcnt(0)
	v_mov_b32_e32 v27, v40
	v_mov_b32_e32 v40, v31
	v_pk_mul_f32 v[30:31], v[28:29], v[40:41] op_sel_hi:[0,1]
	v_pk_fma_f32 v[26:27], v[24:25], v[26:27], v[30:31] op_sel_hi:[0,1,1]
	v_mov_b32_e32 v31, v42
	v_mov_b32_e32 v42, v33
	v_mov_b32_e32 v30, v32
	v_pk_mul_f32 v[32:33], v[34:35], v[42:43] op_sel_hi:[0,1]
	v_pk_fma_f32 v[30:31], v[0:1], v[30:31], v[32:33] op_sel_hi:[0,1,1]
	v_pk_add_f32 v[26:27], v[26:27], v[30:31]
	ds_read_b128 v[30:33], v38 offset:16400
	v_pk_add_f32 v[40:41], v[22:23], v[26:27]
	v_mov_b32_e32 v25, v34
	v_mov_b32_e32 v29, v0
	v_mov_b32_e32 v26, v6
	s_waitcnt lgkmcnt(0)
	v_mov_b32_e32 v22, v31
	v_mov_b32_e32 v31, v33
	v_mov_b32_e32 v23, v32
	v_pk_mul_f32 v[24:25], v[24:25], v[30:31]
	s_nop 0
	v_pk_fma_f32 v[22:23], v[28:29], v[22:23], v[24:25]
	s_nop 0
	v_add_f32_e32 v0, v22, v23
	v_add_co_u32_e32 v22, vcc, s23, v20
	s_mov_b32 s23, 0xfffb8000
	s_nop 0
	v_addc_co_u32_e32 v23, vcc, -1, v21, vcc
	s_waitcnt vmcnt(4)
	v_mov_b32_e32 v28, v108
	v_add_co_u32_e32 v22, vcc, s23, v20
	s_mov_b32 s23, 0xfffc4000
	s_nop 0
	v_addc_co_u32_e32 v23, vcc, -1, v21, vcc
	v_mov_b32_e32 v30, v109
	v_add_co_u32_e32 v22, vcc, s23, v20
	s_mov_b32 s23, 0xfffd0000
	s_nop 0
	v_addc_co_u32_e32 v23, vcc, -1, v21, vcc
	v_add_f32_e32 v33, v39, v0
	v_mov_b32_e32 v0, v110
	v_add_co_u32_e32 v22, vcc, s23, v20
	s_mov_b32 s23, 0xfffdc000
	s_nop 0
	v_addc_co_u32_e32 v23, vcc, -1, v21, vcc
	v_mov_b32_e32 v32, v111
	ds_read_b128 v[22:25], v38 offset:2080
	s_waitcnt lgkmcnt(0)
	v_mov_b32_e32 v27, v22
	v_mov_b32_e32 v22, v7
	v_pk_mul_f32 v[6:7], v[30:31], v[22:23] op_sel_hi:[0,1]
	v_mov_b32_e32 v23, v24
	v_mov_b32_e32 v24, v9
	v_mov_b32_e32 v22, v8
	v_pk_fma_f32 v[6:7], v[28:29], v[26:27], v[6:7] op_sel_hi:[0,1,1]
	v_pk_mul_f32 v[8:9], v[32:33], v[24:25] op_sel_hi:[0,1]
	v_pk_fma_f32 v[8:9], v[0:1], v[22:23], v[8:9] op_sel_hi:[0,1,1]
	v_pk_add_f32 v[6:7], v[6:7], v[8:9]
	s_nop 0
	v_pk_add_f32 v[22:23], v[10:11], v[6:7]
	ds_read_b128 v[6:9], v38 offset:4128
	ds_read_b128 v[24:27], v38 offset:6176
	s_waitcnt lgkmcnt(1)
	v_mov_b32_e32 v10, v6
	s_waitcnt lgkmcnt(0)
	v_mov_b32_e32 v11, v24
	v_mov_b32_e32 v24, v7
	v_pk_mul_f32 v[6:7], v[30:31], v[24:25] op_sel_hi:[0,1]
	v_pk_fma_f32 v[6:7], v[28:29], v[10:11], v[6:7] op_sel_hi:[0,1,1]
	v_mov_b32_e32 v11, v26
	v_mov_b32_e32 v26, v9
	v_mov_b32_e32 v10, v8
	v_pk_mul_f32 v[8:9], v[32:33], v[26:27] op_sel_hi:[0,1]
	v_pk_fma_f32 v[8:9], v[0:1], v[10:11], v[8:9] op_sel_hi:[0,1,1]
	v_pk_add_f32 v[6:7], v[6:7], v[8:9]
	s_nop 0
	v_pk_add_f32 v[12:13], v[12:13], v[6:7]
	ds_read_b128 v[6:9], v38 offset:8224
	ds_read_b128 v[24:27], v38 offset:10272
	s_waitcnt lgkmcnt(1)
	v_mov_b32_e32 v10, v6
	s_waitcnt lgkmcnt(0)
	v_mov_b32_e32 v11, v24
	v_mov_b32_e32 v24, v7
	v_pk_mul_f32 v[6:7], v[30:31], v[24:25] op_sel_hi:[0,1]
	v_pk_fma_f32 v[6:7], v[28:29], v[10:11], v[6:7] op_sel_hi:[0,1,1]
	v_mov_b32_e32 v11, v26
	v_mov_b32_e32 v26, v9
	v_mov_b32_e32 v10, v8
	v_pk_mul_f32 v[8:9], v[32:33], v[26:27] op_sel_hi:[0,1]
	v_pk_fma_f32 v[8:9], v[0:1], v[10:11], v[8:9] op_sel_hi:[0,1,1]
	v_pk_add_f32 v[6:7], v[6:7], v[8:9]
	s_nop 0
	v_pk_add_f32 v[10:11], v[44:45], v[6:7]
	ds_read_b128 v[6:9], v38 offset:12320
	ds_read_b128 v[24:27], v38 offset:14368
	s_waitcnt lgkmcnt(1)
	v_mov_b32_e32 v42, v6
	s_waitcnt lgkmcnt(0)
	v_mov_b32_e32 v43, v24
	v_mov_b32_e32 v24, v7
	v_pk_mul_f32 v[6:7], v[30:31], v[24:25] op_sel_hi:[0,1]
	v_mov_b32_e32 v25, v26
	v_mov_b32_e32 v26, v9
	v_mov_b32_e32 v24, v8
	v_pk_mul_f32 v[8:9], v[32:33], v[26:27] op_sel_hi:[0,1]
	v_pk_fma_f32 v[8:9], v[0:1], v[24:25], v[8:9] op_sel_hi:[0,1,1]
	ds_read_b128 v[24:27], v38 offset:16416
	v_pk_fma_f32 v[6:7], v[28:29], v[42:43], v[6:7] op_sel_hi:[0,1,1]
	v_pk_add_f32 v[6:7], v[6:7], v[8:9]
	v_mov_b32_e32 v29, v32
	v_pk_add_f32 v[8:9], v[40:41], v[6:7]
	s_waitcnt lgkmcnt(0)
	v_mov_b32_e32 v6, v25
	v_mov_b32_e32 v25, v27
	v_mov_b32_e32 v31, v0
	v_mov_b32_e32 v7, v26
	v_pk_mul_f32 v[24:25], v[28:29], v[24:25]
	v_mov_b32_e32 v28, v2
	v_pk_fma_f32 v[6:7], v[30:31], v[6:7], v[24:25]
	s_nop 0
	v_add_f32_e32 v0, v6, v7
	v_add_co_u32_e32 v6, vcc, s23, v20
	s_mov_b32 s23, 0xfffe8000
	s_nop 0
	v_addc_co_u32_e32 v7, vcc, -1, v21, vcc
	v_add_co_u32_e32 v24, vcc, s23, v20
	s_mov_b32 s23, 0xffff4000
	s_nop 0
	v_addc_co_u32_e32 v25, vcc, -1, v21, vcc
	s_waitcnt vmcnt(0)
	v_mov_b32_e32 v6, v112
	v_add_f32_e32 v33, v33, v0
	v_mov_b32_e32 v30, v113
	v_add_co_u32_e32 v24, vcc, s23, v20
	s_nop 1
	v_addc_co_u32_e32 v25, vcc, -1, v21, vcc
	v_mov_b32_e32 v0, v114
	v_mov_b32_e32 v32, v115
	ds_read_b128 v[24:27], v38 offset:2096
	v_lshl_add_u64 v[20:21], v[20:21], 0, s[26:27]
	s_waitcnt lgkmcnt(0)
	v_mov_b32_e32 v29, v24
	v_mov_b32_e32 v24, v3
	v_pk_mul_f32 v[2:3], v[30:31], v[24:25] op_sel_hi:[0,1]
	v_mov_b32_e32 v25, v26
	v_mov_b32_e32 v26, v5
	v_mov_b32_e32 v24, v4
	v_pk_fma_f32 v[2:3], v[6:7], v[28:29], v[2:3] op_sel_hi:[0,1,1]
	v_pk_mul_f32 v[4:5], v[32:33], v[26:27] op_sel_hi:[0,1]
	v_pk_fma_f32 v[4:5], v[0:1], v[24:25], v[4:5] op_sel_hi:[0,1,1]
	v_pk_add_f32 v[2:3], v[2:3], v[4:5]
	s_nop 0
	v_pk_add_f32 v[22:23], v[22:23], v[2:3]
	ds_read_b128 v[2:5], v38 offset:4144
	ds_read_b128 v[24:27], v38 offset:6192
	s_waitcnt lgkmcnt(1)
	v_mov_b32_e32 v28, v2
	s_waitcnt lgkmcnt(0)
	v_mov_b32_e32 v29, v24
	v_mov_b32_e32 v24, v3
	v_pk_mul_f32 v[2:3], v[30:31], v[24:25] op_sel_hi:[0,1]
	v_mov_b32_e32 v25, v26
	v_mov_b32_e32 v26, v5
	v_mov_b32_e32 v24, v4
	v_pk_mul_f32 v[4:5], v[32:33], v[26:27] op_sel_hi:[0,1]
	v_pk_fma_f32 v[2:3], v[6:7], v[28:29], v[2:3] op_sel_hi:[0,1,1]
	v_pk_fma_f32 v[4:5], v[0:1], v[24:25], v[4:5] op_sel_hi:[0,1,1]
	v_pk_add_f32 v[2:3], v[2:3], v[4:5]
	s_nop 0
	v_pk_add_f32 v[24:25], v[12:13], v[2:3]
	ds_read_b128 v[2:5], v38 offset:8240
	ds_read_b128 v[26:29], v38 offset:10288
	s_waitcnt lgkmcnt(1)
	v_mov_b32_e32 v12, v2
	s_waitcnt lgkmcnt(0)
	v_mov_b32_e32 v13, v26
	v_mov_b32_e32 v26, v3
	v_pk_mul_f32 v[2:3], v[30:31], v[26:27] op_sel_hi:[0,1]
	v_pk_fma_f32 v[2:3], v[6:7], v[12:13], v[2:3] op_sel_hi:[0,1,1]
	v_mov_b32_e32 v13, v28
	v_mov_b32_e32 v28, v5
	v_mov_b32_e32 v12, v4
	v_pk_mul_f32 v[4:5], v[32:33], v[28:29] op_sel_hi:[0,1]
	v_pk_fma_f32 v[4:5], v[0:1], v[12:13], v[4:5] op_sel_hi:[0,1,1]
	v_pk_add_f32 v[2:3], v[2:3], v[4:5]
	s_nop 0
	v_pk_add_f32 v[26:27], v[10:11], v[2:3]
	ds_read_b128 v[2:5], v38 offset:12336
	ds_read_b128 v[10:13], v38 offset:14384
	s_waitcnt lgkmcnt(1)
	v_mov_b32_e32 v28, v2
	s_waitcnt lgkmcnt(0)
	v_mov_b32_e32 v29, v10
	v_mov_b32_e32 v10, v3
	v_pk_mul_f32 v[2:3], v[30:31], v[10:11] op_sel_hi:[0,1]
	v_mov_b32_e32 v11, v12
	v_mov_b32_e32 v12, v5
	v_mov_b32_e32 v10, v4
	v_pk_mul_f32 v[4:5], v[32:33], v[12:13] op_sel_hi:[0,1]
	v_pk_fma_f32 v[2:3], v[6:7], v[28:29], v[2:3] op_sel_hi:[0,1,1]
	v_pk_fma_f32 v[4:5], v[0:1], v[10:11], v[4:5] op_sel_hi:[0,1,1]
	v_pk_add_f32 v[2:3], v[2:3], v[4:5]
	v_mov_b32_e32 v7, v32
	v_pk_add_f32 v[28:29], v[8:9], v[2:3]
	ds_read_b128 v[2:5], v38 offset:16432
	v_mov_b32_e32 v31, v0
	v_add_u32_e32 v38, 64, v38
	s_waitcnt lgkmcnt(0)
	v_mov_b32_e32 v8, v3
	v_mov_b32_e32 v3, v5
	v_mov_b32_e32 v9, v4
	v_pk_mul_f32 v[2:3], v[6:7], v[2:3]
	s_nop 0
	v_pk_fma_f32 v[2:3], v[30:31], v[8:9], v[2:3]
	s_nop 0
	v_add_f32_e32 v0, v2, v3
	v_add_f32_e32 v0, v33, v0
	s_cbranch_scc0 .LBB0_1022
	v_add_u32_e32 v2, 0xa000, v37
	ds_write2_b32 v2, v22, v23 offset1:32
	ds_write2_b32 v2, v24, v25 offset0:64 offset1:96
	ds_write2_b32 v2, v26, v27 offset0:128 offset1:160
	ds_write2_b32 v2, v28, v29 offset0:192 offset1:224
	ds_write_b32 v37, v0 offset:41984
	s_waitcnt lgkmcnt(0)
	s_barrier
	s_and_saveexec_b64 s[22:23], s[38:39]
	s_cbranch_execz .LBB0_1020
	s_mul_i32 s25, s24, 0x1800
	s_add_i32 s26, s25, s0
	v_or_b32_e32 v2, s26, v14
	v_readlane_b32 s56, v253, 6
	v_ashrrev_i32_e32 v3, 31, v2
	v_readlane_b32 s58, v253, 8
	v_readlane_b32 s59, v253, 9
	v_readlane_b32 s64, v253, 14
	v_readlane_b32 s65, v253, 15
	s_mul_hi_i32 s25, s24, 9
	s_mul_i32 s24, s24, 9
	v_readlane_b32 s64, v253, 49
	v_lshl_add_u64 v[2:3], v[2:3], 2, s[58:59]
	v_lshl_add_u64 v[4:5], s[0:1], 2, v[16:17]
	s_mov_b64 s[0:1], 0
	v_mov_b32_e32 v0, v184
	v_readlane_b32 s57, v253, 7
	v_readlane_b32 s60, v253, 10
	v_readlane_b32 s61, v253, 11
	v_readlane_b32 s62, v253, 12
	v_readlane_b32 s63, v253, 13
	v_readlane_b32 s66, v253, 16
	v_readlane_b32 s67, v253, 17
	v_readlane_b32 s68, v253, 18
	v_readlane_b32 s69, v253, 19
	v_readlane_b32 s70, v253, 20
	v_readlane_b32 s71, v253, 21
	v_readlane_b32 s65, v253, 50

.LBB0_1037:
	s_andn2_b64 vcc, exec, s[0:1]
	s_cbranch_vccnz .LBB0_1039
	s_add_i32 s0, s86, 0xffffbe00
	s_cmpk_gt_u32 s0, 0x2ff
	v_readlane_b32 s36, v253, 6
	s_cselect_b32 s1, 0x600000, 0
	v_readlane_b32 s40, v253, 10
	s_cselect_b32 s8, 0x300000, 0
	v_readlane_b32 s41, v253, 11
	s_add_u32 s1, s40, s1
	s_addc_u32 s27, s41, 0
	v_readlane_b32 s7, v251, 36
	s_add_u32 s25, s7, s8
	v_readlane_b32 s7, v251, 37
	s_addc_u32 s26, s7, 0
	s_add_i32 s8, s86, 0xbb00
	s_cmpk_lt_u32 s0, 0x300
	s_cselect_b32 s0, s0, s8
	s_sext_i32_i16 s8, s0
	s_mulk_i32 s8, 0x2aab
	s_lshr_b32 s28, s8, 31
	s_ashr_i32 s8, s8, 19
	s_add_i32 s29, s8, s28
	s_mul_i32 s8, s29, 48
	s_sub_i32 s0, s0, s8
	s_sext_i32_i16 s0, s0
	s_lshl_b32 s28, s0, 5
	s_lshl_b32 s30, s0, 7
	s_and_b32 s8, s28, 0xffffff00
	s_and_b32 s30, s30, 0x80
	s_lshl_b32 s0, s0, 4
	s_or_b32 s8, s8, s30
	s_and_b32 s0, s0, 0x60
	s_or_b32 s8, s8, s0
	s_lshl_b32 s0, s29, 6
	s_ashr_i32 s29, s28, 31
	s_lshl_b64 s[28:29], s[28:29], 2
	s_add_u32 s28, s1, s28
	s_addc_u32 s29, s27, s29
	v_lshlrev_b32_e32 v0, 2, v14
	v_lshl_add_u64 v[4:5], s[28:29], 0, v[0:1]
	v_or_b32_e32 v0, s0, v15
	v_mul_i32_i24_e32 v50, 0x600, v0
	v_ashrrev_i32_e32 v51, 31, v50
	v_lshl_add_u64 v[50:51], v[50:51], 2, v[4:5]
	global_load_dword v100, v[50:51], off
	v_or_b32_e32 v50, s0, v7
	v_mul_i32_i24_e32 v50, 0x600, v50
	v_ashrrev_i32_e32 v51, 31, v50
	v_lshl_add_u64 v[50:51], v[50:51], 2, v[4:5]
	global_load_dword v101, v[50:51], off
	s_ashr_i32 s1, s0, 31
	v_or_b32_e32 v70, s8, v44
	v_ashrrev_i32_e32 v71, 31, v70
	v_lshlrev_b64 v[70:71], 11, v[70:71]
	v_readlane_b32 s37, v253, 7
	v_readlane_b32 s38, v253, 8
	v_readlane_b32 s39, v253, 9
	v_readlane_b32 s42, v253, 12
	v_readlane_b32 s43, v253, 13
	v_readlane_b32 s44, v253, 14
	v_readlane_b32 s45, v253, 15
	v_readlane_b32 s46, v253, 16
	v_readlane_b32 s47, v253, 17
	v_readlane_b32 s48, v253, 18
	v_readlane_b32 s49, v253, 19
	v_readlane_b32 s50, v253, 20
	v_readlane_b32 s51, v253, 21
	v_or_b32_e32 v0, s0, v8
	v_mul_i32_i24_e32 v50, 0x600, v0
	v_ashrrev_i32_e32 v51, 31, v50
	v_lshl_add_u64 v[50:51], v[50:51], 2, v[4:5]
	global_load_dword v102, v[50:51], off
	v_or_b32_e32 v50, s0, v9
	v_mul_i32_i24_e32 v50, 0x600, v50
	v_ashrrev_i32_e32 v51, 31, v50
	v_lshl_add_u64 v[50:51], v[50:51], 2, v[4:5]
	global_load_dword v103, v[50:51], off
	v_or_b32_e32 v0, s0, v10
	v_mul_i32_i24_e32 v50, 0x600, v0
	v_ashrrev_i32_e32 v51, 31, v50
	v_lshl_add_u64 v[50:51], v[50:51], 2, v[4:5]
	global_load_dword v104, v[50:51], off
	v_or_b32_e32 v50, s0, v11
	v_mul_i32_i24_e32 v50, 0x600, v50
	v_ashrrev_i32_e32 v51, 31, v50
	v_lshl_add_u64 v[50:51], v[50:51], 2, v[4:5]
	global_load_dword v105, v[50:51], off
	v_or_b32_e32 v0, s0, v12
	v_mul_i32_i24_e32 v50, 0x600, v0
	v_ashrrev_i32_e32 v51, 31, v50
	v_lshl_add_u64 v[50:51], v[50:51], 2, v[4:5]
	global_load_dword v106, v[50:51], off
	v_or_b32_e32 v50, s0, v16
	v_mul_i32_i24_e32 v50, 0x600, v50
	v_ashrrev_i32_e32 v51, 31, v50
	v_lshl_add_u64 v[50:51], v[50:51], 2, v[4:5]
	global_load_dword v107, v[50:51], off
	v_or_b32_e32 v0, s0, v17
	v_mul_i32_i24_e32 v50, 0x600, v0
	v_ashrrev_i32_e32 v51, 31, v50
	v_lshl_add_u64 v[50:51], v[50:51], 2, v[4:5]
	global_load_dword v108, v[50:51], off
	v_or_b32_e32 v50, s0, v18
	v_mul_i32_i24_e32 v50, 0x600, v50
	v_ashrrev_i32_e32 v51, 31, v50
	v_lshl_add_u64 v[50:51], v[50:51], 2, v[4:5]
	global_load_dword v109, v[50:51], off
	v_or_b32_e32 v0, s0, v19
	v_mul_i32_i24_e32 v50, 0x600, v0
	v_ashrrev_i32_e32 v51, 31, v50
	v_lshl_add_u64 v[50:51], v[50:51], 2, v[4:5]
	global_load_dword v110, v[50:51], off
	v_or_b32_e32 v50, s0, v20
	v_mul_i32_i24_e32 v50, 0x600, v50
	v_ashrrev_i32_e32 v51, 31, v50
	v_lshl_add_u64 v[50:51], v[50:51], 2, v[4:5]
	global_load_dword v111, v[50:51], off
	v_or_b32_e32 v0, s0, v21
	v_mul_i32_i24_e32 v50, 0x600, v0
	v_ashrrev_i32_e32 v51, 31, v50
	v_lshl_add_u64 v[50:51], v[50:51], 2, v[4:5]
	global_load_dword v112, v[50:51], off
	v_or_b32_e32 v50, s0, v23
	v_mul_i32_i24_e32 v50, 0x600, v50
	v_ashrrev_i32_e32 v51, 31, v50
	v_lshl_add_u64 v[50:51], v[50:51], 2, v[4:5]
	global_load_dword v113, v[50:51], off
	v_or_b32_e32 v0, s0, v24
	v_mul_i32_i24_e32 v50, 0x600, v0
	v_ashrrev_i32_e32 v51, 31, v50
	v_lshl_add_u64 v[50:51], v[50:51], 2, v[4:5]
	global_load_dword v114, v[50:51], off
	v_or_b32_e32 v50, s0, v25
	v_mul_i32_i24_e32 v50, 0x600, v50
	v_ashrrev_i32_e32 v51, 31, v50
	v_lshl_add_u64 v[50:51], v[50:51], 2, v[4:5]
	global_load_dword v115, v[50:51], off
	v_or_b32_e32 v0, s0, v26
	v_mul_i32_i24_e32 v50, 0x600, v0
	v_ashrrev_i32_e32 v51, 31, v50
	v_lshl_add_u64 v[50:51], v[50:51], 2, v[4:5]
	global_load_dword v116, v[50:51], off
	v_or_b32_e32 v50, s0, v27
	v_mul_i32_i24_e32 v50, 0x600, v50
	v_ashrrev_i32_e32 v51, 31, v50
	v_lshl_add_u64 v[50:51], v[50:51], 2, v[4:5]
	global_load_dword v117, v[50:51], off
	v_or_b32_e32 v0, s0, v28
	v_mul_i32_i24_e32 v50, 0x600, v0
	v_ashrrev_i32_e32 v51, 31, v50
	v_lshl_add_u64 v[50:51], v[50:51], 2, v[4:5]
	global_load_dword v118, v[50:51], off
	v_or_b32_e32 v50, s0, v30
	v_mul_i32_i24_e32 v50, 0x600, v50
	v_ashrrev_i32_e32 v51, 31, v50
	v_lshl_add_u64 v[50:51], v[50:51], 2, v[4:5]
	global_load_dword v119, v[50:51], off
	v_or_b32_e32 v0, s0, v31
	v_mul_i32_i24_e32 v50, 0x600, v0
	v_ashrrev_i32_e32 v51, 31, v50
	v_lshl_add_u64 v[50:51], v[50:51], 2, v[4:5]
	global_load_dword v120, v[50:51], off
	v_or_b32_e32 v50, s0, v32
	v_mul_i32_i24_e32 v50, 0x600, v50
	v_ashrrev_i32_e32 v51, 31, v50
	v_lshl_add_u64 v[50:51], v[50:51], 2, v[4:5]
	global_load_dword v121, v[50:51], off
	v_or_b32_e32 v0, s0, v33
	v_mul_i32_i24_e32 v50, 0x600, v0
	v_ashrrev_i32_e32 v51, 31, v50
	v_lshl_add_u64 v[50:51], v[50:51], 2, v[4:5]
	global_load_dword v122, v[50:51], off
	v_or_b32_e32 v50, s0, v34
	v_mul_i32_i24_e32 v50, 0x600, v50
	v_ashrrev_i32_e32 v51, 31, v50
	v_lshl_add_u64 v[50:51], v[50:51], 2, v[4:5]
	global_load_dword v123, v[50:51], off
	v_or_b32_e32 v0, s0, v35
	v_mul_i32_i24_e32 v50, 0x600, v0
	v_ashrrev_i32_e32 v51, 31, v50
	v_lshl_add_u64 v[50:51], v[50:51], 2, v[4:5]
	global_load_dword v124, v[50:51], off
	v_or_b32_e32 v50, s0, v37
	v_mul_i32_i24_e32 v50, 0x600, v50
	v_ashrrev_i32_e32 v51, 31, v50
	v_lshl_add_u64 v[50:51], v[50:51], 2, v[4:5]
	global_load_dword v125, v[50:51], off
	v_or_b32_e32 v0, s0, v38
	v_mul_i32_i24_e32 v50, 0x600, v0
	v_ashrrev_i32_e32 v51, 31, v50
	v_lshl_add_u64 v[50:51], v[50:51], 2, v[4:5]
	global_load_dword v126, v[50:51], off
	v_or_b32_e32 v50, s0, v39
	v_mul_i32_i24_e32 v50, 0x600, v50
	v_ashrrev_i32_e32 v51, 31, v50
	v_lshl_add_u64 v[50:51], v[50:51], 2, v[4:5]
	global_load_dword v127, v[50:51], off
	v_or_b32_e32 v0, s0, v40
	v_mul_i32_i24_e32 v50, 0x600, v0
	v_ashrrev_i32_e32 v51, 31, v50
	v_lshl_add_u64 v[50:51], v[50:51], 2, v[4:5]
	global_load_dword v128, v[50:51], off
	v_or_b32_e32 v50, s0, v41
	v_mul_i32_i24_e32 v50, 0x600, v50
	v_ashrrev_i32_e32 v51, 31, v50
	v_lshl_add_u64 v[50:51], v[50:51], 2, v[4:5]
	global_load_dword v129, v[50:51], off
	v_or_b32_e32 v0, s0, v42
	v_mul_i32_i24_e32 v50, 0x600, v0
	v_ashrrev_i32_e32 v51, 31, v50
	v_lshl_add_u64 v[50:51], v[50:51], 2, v[4:5]
	global_load_dword v130, v[50:51], off
	v_or_b32_e32 v50, s0, v43
	v_mul_i32_i24_e32 v50, 0x600, v50
	v_ashrrev_i32_e32 v51, 31, v50
	v_lshl_add_u64 v[4:5], v[50:51], 2, v[4:5]
	global_load_dword v131, v[4:5], off
	s_lshl_b64 s[0:1], s[0:1], 1
	s_add_u32 s0, s25, s0
	s_addc_u32 s1, s26, s1
	s_waitcnt vmcnt(0)
	v_add_u32_e32 v49, v3, v6
	ds_write2_b32 v49, v100, v101 offset1:66
	ds_write2_b32 v49, v102, v103 offset0:132 offset1:198
	v_add_u32_e32 v49, 0x400, v49
	ds_write2_b32 v49, v104, v105 offset0:8 offset1:74
	v_add_u32_e32 v49, v3, v13
	ds_write2_b32 v49, v106, v107 offset1:66
	ds_write2_b32 v49, v108, v109 offset0:132 offset1:198
	v_add_u32_e32 v49, 0x400, v49
	ds_write2_b32 v49, v110, v111 offset0:8 offset1:74
	v_add_u32_e32 v49, v3, v22
	ds_write2_b32 v49, v112, v113 offset1:66
	ds_write2_b32 v49, v114, v115 offset0:132 offset1:198
	v_add_u32_e32 v49, 0x400, v49
	ds_write2_b32 v49, v116, v117 offset0:8 offset1:74
	v_add_u32_e32 v49, v3, v29
	ds_write2_b32 v49, v118, v119 offset1:66
	ds_write2_b32 v49, v120, v121 offset0:132 offset1:198
	v_add_u32_e32 v49, 0x400, v49
	ds_write2_b32 v49, v122, v123 offset0:8 offset1:74
	v_add_u32_e32 v49, v3, v36
	ds_write2_b32 v49, v124, v125 offset1:66
	ds_write2_b32 v49, v126, v127 offset0:132 offset1:198
	v_add_u32_e32 v49, 0x400, v49
	ds_write2_b32 v49, v128, v129 offset0:8 offset1:74
	ds_write2_b32 v49, v130, v131 offset0:140 offset1:206
	s_waitcnt lgkmcnt(0)
	ds_read2_b32 v[54:55], v45 offset0:33 offset1:41
	ds_read2_b32 v[56:57], v45 offset1:8
	ds_read2_b32 v[58:59], v45 offset0:66 offset1:74
	ds_read2_b32 v[60:61], v45 offset0:99 offset1:107
	ds_read2_b32 v[62:63], v45 offset0:132 offset1:140
	ds_read2_b32 v[64:65], v45 offset0:165 offset1:173
	ds_read2_b32 v[66:67], v45 offset0:198 offset1:206
	ds_read2_b32 v[68:69], v45 offset0:231 offset1:239
	v_lshlrev_b32_e32 v0, 1, v2
	v_lshl_add_u64 v[4:5], s[0:1], 0, v[0:1]
	s_waitcnt lgkmcnt(6)
	v_cvt_pk_bf16_f32 v50, v56, v54
	s_waitcnt lgkmcnt(4)
	v_cvt_pk_bf16_f32 v51, v58, v60
	s_waitcnt lgkmcnt(2)
	v_cvt_pk_bf16_f32 v52, v62, v64
	s_waitcnt lgkmcnt(0)
	v_cvt_pk_bf16_f32 v53, v66, v68
	v_lshl_add_u64 v[70:71], v[4:5], 0, v[70:71]
	v_or_b32_e32 v54, s8, v46
	global_store_dwordx4 v[70:71], v[50:53], off
	v_or_b32_e32 v70, s8, v47
	v_ashrrev_i32_e32 v71, 31, v70
	v_cvt_pk_bf16_f32 v50, v57, v55
	v_ashrrev_i32_e32 v55, 31, v54
	v_lshlrev_b64 v[54:55], 11, v[54:55]
	v_cvt_pk_bf16_f32 v51, v59, v61
	v_cvt_pk_bf16_f32 v52, v63, v65
	v_cvt_pk_bf16_f32 v53, v67, v69
	v_lshl_add_u64 v[54:55], v[4:5], 0, v[54:55]
	global_store_dwordx4 v[54:55], v[50:53], off
	ds_read2_b32 v[54:55], v45 offset0:49 offset1:57
	ds_read2_b32 v[56:57], v45 offset0:16 offset1:24
	ds_read2_b32 v[58:59], v45 offset0:82 offset1:90
	ds_read2_b32 v[60:61], v45 offset0:115 offset1:123
	ds_read2_b32 v[62:63], v45 offset0:148 offset1:156
	ds_read2_b32 v[64:65], v45 offset0:181 offset1:189
	ds_read2_b32 v[66:67], v45 offset0:214 offset1:222
	ds_read2_b32 v[68:69], v45 offset0:247 offset1:255
	v_lshlrev_b64 v[70:71], 11, v[70:71]
	s_waitcnt lgkmcnt(6)
	v_cvt_pk_bf16_f32 v50, v56, v54
	s_waitcnt lgkmcnt(4)
	v_cvt_pk_bf16_f32 v51, v58, v60
	s_waitcnt lgkmcnt(2)
	v_cvt_pk_bf16_f32 v52, v62, v64
	s_waitcnt lgkmcnt(0)
	v_cvt_pk_bf16_f32 v53, v66, v68
	v_lshl_add_u64 v[70:71], v[4:5], 0, v[70:71]
	v_or_b32_e32 v54, s8, v48
	global_store_dwordx4 v[70:71], v[50:53], off
	s_nop 1
	v_cvt_pk_bf16_f32 v50, v57, v55
	v_ashrrev_i32_e32 v55, 31, v54
	v_lshlrev_b64 v[54:55], 11, v[54:55]
	v_cvt_pk_bf16_f32 v51, v59, v61
	v_cvt_pk_bf16_f32 v52, v63, v65
	v_cvt_pk_bf16_f32 v53, v67, v69
	v_lshl_add_u64 v[4:5], v[4:5], 0, v[54:55]
	global_store_dwordx4 v[4:5], v[50:53], off
	s_waitcnt lgkmcnt(0)

.LBB0_1043:
	s_andn2_b64 vcc, exec, s[0:1]
	s_cbranch_vccnz .LBB0_1028
	s_mul_hi_i32 s0, s86, 0x2e8ba2e9
	s_lshr_b32 s1, s0, 31
	s_ashr_i32 s0, s0, 9
	s_add_i32 s0, s0, s1
	v_readlane_b32 s56, v251, 1
	s_mul_i32 s8, s0, 0x1600000
	v_readlane_b32 s60, v251, 5
	s_mul_hi_i32 s1, s0, 0x1600000
	v_readlane_b32 s61, v251, 6
	s_add_u32 s27, s60, s8
	s_addc_u32 s1, s61, s1
	s_mul_i32 s25, s0, 0xb00000
	v_readlane_b32 s7, v251, 28
	s_mul_hi_i32 s8, s0, 0xb00000
	s_add_u32 s25, s7, s25
	v_readlane_b32 s7, v251, 29
	s_mulk_i32 s0, 0xf500
	s_addc_u32 s26, s7, s8
	s_add_i32 s0, s86, s0
	s_mul_i32 s8, s0, 0xba3
	s_lshr_b32 s28, s8, 31
	s_ashr_i32 s8, s8, 19
	s_add_i32 s29, s8, s28
	s_mul_i32 s8, s29, 0xb0
	s_sub_i32 s0, s0, s8
	s_sext_i32_i16 s0, s0
	s_lshl_b32 s28, s0, 5
	s_cmpk_gt_i32 s0, 0x57
	s_cselect_b32 s0, 0xfffff500, 0
	s_cselect_b32 s8, 0x80, 0
	s_add_i32 s0, s0, s28
	s_lshl_b32 s0, s0, 1
	s_and_b32 s30, s28, 0x60
	s_and_b32 s0, s0, 0xffffff00
	s_or_b32 s8, s30, s8
	s_or_b32 s8, s8, s0
	s_lshl_b32 s0, s29, 6
	s_ashr_i32 s29, s28, 31
	s_lshl_b64 s[28:29], s[28:29], 2
	s_add_u32 s28, s27, s28
	s_addc_u32 s29, s1, s29
	v_lshlrev_b32_e32 v0, 2, v14
	v_lshl_add_u64 v[4:5], s[28:29], 0, v[0:1]
	v_or_b32_e32 v0, s0, v15
	v_mul_i32_i24_e32 v50, 0x1600, v0
	v_ashrrev_i32_e32 v51, 31, v50
	v_lshl_add_u64 v[50:51], v[50:51], 2, v[4:5]
	global_load_dword v100, v[50:51], off
	v_or_b32_e32 v50, s0, v7
	v_mul_i32_i24_e32 v50, 0x1600, v50
	v_ashrrev_i32_e32 v51, 31, v50
	v_lshl_add_u64 v[50:51], v[50:51], 2, v[4:5]
	global_load_dword v101, v[50:51], off
	s_ashr_i32 s1, s0, 31
	v_or_b32_e32 v70, s8, v44
	v_ashrrev_i32_e32 v71, 31, v70
	v_lshlrev_b64 v[70:71], 11, v[70:71]
	v_readlane_b32 s64, v251, 9
	v_readlane_b32 s65, v251, 10
	v_readlane_b32 s64, v253, 49
	v_readlane_b32 s57, v251, 2
	v_readlane_b32 s58, v251, 3
	v_readlane_b32 s59, v251, 4
	v_readlane_b32 s62, v251, 7
	v_readlane_b32 s63, v251, 8
	v_readlane_b32 s66, v251, 11
	v_readlane_b32 s67, v251, 12
	v_readlane_b32 s68, v251, 13
	v_readlane_b32 s69, v251, 14
	v_readlane_b32 s70, v251, 15
	v_readlane_b32 s71, v251, 16
	v_readlane_b32 s65, v253, 50
	v_or_b32_e32 v0, s0, v8
	v_mul_i32_i24_e32 v50, 0x1600, v0
	v_ashrrev_i32_e32 v51, 31, v50
	v_lshl_add_u64 v[50:51], v[50:51], 2, v[4:5]
	global_load_dword v102, v[50:51], off
	v_or_b32_e32 v50, s0, v9
	v_mul_i32_i24_e32 v50, 0x1600, v50
	v_ashrrev_i32_e32 v51, 31, v50
	v_lshl_add_u64 v[50:51], v[50:51], 2, v[4:5]
	global_load_dword v103, v[50:51], off
	v_or_b32_e32 v0, s0, v10
	v_mul_i32_i24_e32 v50, 0x1600, v0
	v_ashrrev_i32_e32 v51, 31, v50
	v_lshl_add_u64 v[50:51], v[50:51], 2, v[4:5]
	global_load_dword v104, v[50:51], off
	v_or_b32_e32 v50, s0, v11
	v_mul_i32_i24_e32 v50, 0x1600, v50
	v_ashrrev_i32_e32 v51, 31, v50
	v_lshl_add_u64 v[50:51], v[50:51], 2, v[4:5]
	global_load_dword v105, v[50:51], off
	v_or_b32_e32 v0, s0, v12
	v_mul_i32_i24_e32 v50, 0x1600, v0
	v_ashrrev_i32_e32 v51, 31, v50
	v_lshl_add_u64 v[50:51], v[50:51], 2, v[4:5]
	global_load_dword v106, v[50:51], off
	v_or_b32_e32 v50, s0, v16
	v_mul_i32_i24_e32 v50, 0x1600, v50
	v_ashrrev_i32_e32 v51, 31, v50
	v_lshl_add_u64 v[50:51], v[50:51], 2, v[4:5]
	global_load_dword v107, v[50:51], off
	v_or_b32_e32 v0, s0, v17
	v_mul_i32_i24_e32 v50, 0x1600, v0
	v_ashrrev_i32_e32 v51, 31, v50
	v_lshl_add_u64 v[50:51], v[50:51], 2, v[4:5]
	global_load_dword v108, v[50:51], off
	v_or_b32_e32 v50, s0, v18
	v_mul_i32_i24_e32 v50, 0x1600, v50
	v_ashrrev_i32_e32 v51, 31, v50
	v_lshl_add_u64 v[50:51], v[50:51], 2, v[4:5]
	global_load_dword v109, v[50:51], off
	v_or_b32_e32 v0, s0, v19
	v_mul_i32_i24_e32 v50, 0x1600, v0
	v_ashrrev_i32_e32 v51, 31, v50
	v_lshl_add_u64 v[50:51], v[50:51], 2, v[4:5]
	global_load_dword v110, v[50:51], off
	v_or_b32_e32 v50, s0, v20
	v_mul_i32_i24_e32 v50, 0x1600, v50
	v_ashrrev_i32_e32 v51, 31, v50
	v_lshl_add_u64 v[50:51], v[50:51], 2, v[4:5]
	global_load_dword v111, v[50:51], off
	v_or_b32_e32 v0, s0, v21
	v_mul_i32_i24_e32 v50, 0x1600, v0
	v_ashrrev_i32_e32 v51, 31, v50
	v_lshl_add_u64 v[50:51], v[50:51], 2, v[4:5]
	global_load_dword v112, v[50:51], off
	v_or_b32_e32 v50, s0, v23
	v_mul_i32_i24_e32 v50, 0x1600, v50
	v_ashrrev_i32_e32 v51, 31, v50
	v_lshl_add_u64 v[50:51], v[50:51], 2, v[4:5]
	global_load_dword v113, v[50:51], off
	v_or_b32_e32 v0, s0, v24
	v_mul_i32_i24_e32 v50, 0x1600, v0
	v_ashrrev_i32_e32 v51, 31, v50
	v_lshl_add_u64 v[50:51], v[50:51], 2, v[4:5]
	global_load_dword v114, v[50:51], off
	v_or_b32_e32 v50, s0, v25
	v_mul_i32_i24_e32 v50, 0x1600, v50
	v_ashrrev_i32_e32 v51, 31, v50
	v_lshl_add_u64 v[50:51], v[50:51], 2, v[4:5]
	global_load_dword v115, v[50:51], off
	v_or_b32_e32 v0, s0, v26
	v_mul_i32_i24_e32 v50, 0x1600, v0
	v_ashrrev_i32_e32 v51, 31, v50
	v_lshl_add_u64 v[50:51], v[50:51], 2, v[4:5]
	global_load_dword v116, v[50:51], off
	v_or_b32_e32 v50, s0, v27
	v_mul_i32_i24_e32 v50, 0x1600, v50
	v_ashrrev_i32_e32 v51, 31, v50
	v_lshl_add_u64 v[50:51], v[50:51], 2, v[4:5]
	global_load_dword v117, v[50:51], off
	v_or_b32_e32 v0, s0, v28
	v_mul_i32_i24_e32 v50, 0x1600, v0
	v_ashrrev_i32_e32 v51, 31, v50
	v_lshl_add_u64 v[50:51], v[50:51], 2, v[4:5]
	global_load_dword v118, v[50:51], off
	v_or_b32_e32 v50, s0, v30
	v_mul_i32_i24_e32 v50, 0x1600, v50
	v_ashrrev_i32_e32 v51, 31, v50
	v_lshl_add_u64 v[50:51], v[50:51], 2, v[4:5]
	global_load_dword v119, v[50:51], off
	v_or_b32_e32 v0, s0, v31
	v_mul_i32_i24_e32 v50, 0x1600, v0
	v_ashrrev_i32_e32 v51, 31, v50
	v_lshl_add_u64 v[50:51], v[50:51], 2, v[4:5]
	global_load_dword v120, v[50:51], off
	v_or_b32_e32 v50, s0, v32
	v_mul_i32_i24_e32 v50, 0x1600, v50
	v_ashrrev_i32_e32 v51, 31, v50
	v_lshl_add_u64 v[50:51], v[50:51], 2, v[4:5]
	global_load_dword v121, v[50:51], off
	v_or_b32_e32 v0, s0, v33
	v_mul_i32_i24_e32 v50, 0x1600, v0
	v_ashrrev_i32_e32 v51, 31, v50
	v_lshl_add_u64 v[50:51], v[50:51], 2, v[4:5]
	global_load_dword v122, v[50:51], off
	v_or_b32_e32 v50, s0, v34
	v_mul_i32_i24_e32 v50, 0x1600, v50
	v_ashrrev_i32_e32 v51, 31, v50
	v_lshl_add_u64 v[50:51], v[50:51], 2, v[4:5]
	global_load_dword v123, v[50:51], off
	v_or_b32_e32 v0, s0, v35
	v_mul_i32_i24_e32 v50, 0x1600, v0
	v_ashrrev_i32_e32 v51, 31, v50
	v_lshl_add_u64 v[50:51], v[50:51], 2, v[4:5]
	global_load_dword v124, v[50:51], off
	v_or_b32_e32 v50, s0, v37
	v_mul_i32_i24_e32 v50, 0x1600, v50
	v_ashrrev_i32_e32 v51, 31, v50
	v_lshl_add_u64 v[50:51], v[50:51], 2, v[4:5]
	global_load_dword v125, v[50:51], off
	v_or_b32_e32 v0, s0, v38
	v_mul_i32_i24_e32 v50, 0x1600, v0
	v_ashrrev_i32_e32 v51, 31, v50
	v_lshl_add_u64 v[50:51], v[50:51], 2, v[4:5]
	global_load_dword v126, v[50:51], off
	v_or_b32_e32 v50, s0, v39
	v_mul_i32_i24_e32 v50, 0x1600, v50
	v_ashrrev_i32_e32 v51, 31, v50
	v_lshl_add_u64 v[50:51], v[50:51], 2, v[4:5]
	global_load_dword v127, v[50:51], off
	v_or_b32_e32 v0, s0, v40
	v_mul_i32_i24_e32 v50, 0x1600, v0
	v_ashrrev_i32_e32 v51, 31, v50
	v_lshl_add_u64 v[50:51], v[50:51], 2, v[4:5]
	global_load_dword v128, v[50:51], off
	v_or_b32_e32 v50, s0, v41
	v_mul_i32_i24_e32 v50, 0x1600, v50
	v_ashrrev_i32_e32 v51, 31, v50
	v_lshl_add_u64 v[50:51], v[50:51], 2, v[4:5]
	global_load_dword v129, v[50:51], off
	v_or_b32_e32 v0, s0, v42
	v_mul_i32_i24_e32 v50, 0x1600, v0
	v_ashrrev_i32_e32 v51, 31, v50
	v_lshl_add_u64 v[50:51], v[50:51], 2, v[4:5]
	global_load_dword v130, v[50:51], off
	v_or_b32_e32 v50, s0, v43
	v_mul_i32_i24_e32 v50, 0x1600, v50
	v_ashrrev_i32_e32 v51, 31, v50
	v_lshl_add_u64 v[4:5], v[50:51], 2, v[4:5]
	global_load_dword v131, v[4:5], off
	s_lshl_b64 s[0:1], s[0:1], 1
	s_add_u32 s0, s25, s0
	s_addc_u32 s1, s26, s1
	s_waitcnt vmcnt(0)
	v_add_u32_e32 v49, v3, v6
	ds_write2_b32 v49, v100, v101 offset1:66
	ds_write2_b32 v49, v102, v103 offset0:132 offset1:198
	v_add_u32_e32 v49, 0x400, v49
	ds_write2_b32 v49, v104, v105 offset0:8 offset1:74
	v_add_u32_e32 v49, v3, v13
	ds_write2_b32 v49, v106, v107 offset1:66
	ds_write2_b32 v49, v108, v109 offset0:132 offset1:198
	v_add_u32_e32 v49, 0x400, v49
	ds_write2_b32 v49, v110, v111 offset0:8 offset1:74
	v_add_u32_e32 v49, v3, v22
	ds_write2_b32 v49, v112, v113 offset1:66
	ds_write2_b32 v49, v114, v115 offset0:132 offset1:198
	v_add_u32_e32 v49, 0x400, v49
	ds_write2_b32 v49, v116, v117 offset0:8 offset1:74
	v_add_u32_e32 v49, v3, v29
	ds_write2_b32 v49, v118, v119 offset1:66
	ds_write2_b32 v49, v120, v121 offset0:132 offset1:198
	v_add_u32_e32 v49, 0x400, v49
	ds_write2_b32 v49, v122, v123 offset0:8 offset1:74
	v_add_u32_e32 v49, v3, v36
	ds_write2_b32 v49, v124, v125 offset1:66
	ds_write2_b32 v49, v126, v127 offset0:132 offset1:198
	v_add_u32_e32 v49, 0x400, v49
	ds_write2_b32 v49, v128, v129 offset0:8 offset1:74
	ds_write2_b32 v49, v130, v131 offset0:140 offset1:206
	s_waitcnt lgkmcnt(0)
	ds_read2_b32 v[54:55], v45 offset0:33 offset1:41
	ds_read2_b32 v[56:57], v45 offset1:8
	ds_read2_b32 v[58:59], v45 offset0:66 offset1:74
	ds_read2_b32 v[60:61], v45 offset0:99 offset1:107
	ds_read2_b32 v[62:63], v45 offset0:132 offset1:140
	ds_read2_b32 v[64:65], v45 offset0:165 offset1:173
	ds_read2_b32 v[66:67], v45 offset0:198 offset1:206
	ds_read2_b32 v[68:69], v45 offset0:231 offset1:239
	v_lshlrev_b32_e32 v0, 1, v2
	v_lshl_add_u64 v[4:5], s[0:1], 0, v[0:1]
	s_waitcnt lgkmcnt(6)
	v_cvt_pk_bf16_f32 v50, v56, v54
	s_waitcnt lgkmcnt(4)
	v_cvt_pk_bf16_f32 v51, v58, v60
	s_waitcnt lgkmcnt(2)
	v_cvt_pk_bf16_f32 v52, v62, v64
	s_waitcnt lgkmcnt(0)
	v_cvt_pk_bf16_f32 v53, v66, v68
	v_lshl_add_u64 v[70:71], v[4:5], 0, v[70:71]
	v_or_b32_e32 v54, s8, v46
	global_store_dwordx4 v[70:71], v[50:53], off
	v_or_b32_e32 v70, s8, v47
	v_ashrrev_i32_e32 v71, 31, v70
	v_cvt_pk_bf16_f32 v50, v57, v55
	v_ashrrev_i32_e32 v55, 31, v54
	v_lshlrev_b64 v[54:55], 11, v[54:55]
	v_cvt_pk_bf16_f32 v51, v59, v61
	v_cvt_pk_bf16_f32 v52, v63, v65
	v_cvt_pk_bf16_f32 v53, v67, v69
	v_lshl_add_u64 v[54:55], v[4:5], 0, v[54:55]
	global_store_dwordx4 v[54:55], v[50:53], off
	ds_read2_b32 v[54:55], v45 offset0:49 offset1:57
	ds_read2_b32 v[56:57], v45 offset0:16 offset1:24
	ds_read2_b32 v[58:59], v45 offset0:82 offset1:90
	ds_read2_b32 v[60:61], v45 offset0:115 offset1:123
	ds_read2_b32 v[62:63], v45 offset0:148 offset1:156
	ds_read2_b32 v[64:65], v45 offset0:181 offset1:189
	ds_read2_b32 v[66:67], v45 offset0:214 offset1:222
	ds_read2_b32 v[68:69], v45 offset0:247 offset1:255
	v_lshlrev_b64 v[70:71], 11, v[70:71]
	s_waitcnt lgkmcnt(6)
	v_cvt_pk_bf16_f32 v50, v56, v54
	s_waitcnt lgkmcnt(4)
	v_cvt_pk_bf16_f32 v51, v58, v60
	s_waitcnt lgkmcnt(2)
	v_cvt_pk_bf16_f32 v52, v62, v64
	s_waitcnt lgkmcnt(0)
	v_cvt_pk_bf16_f32 v53, v66, v68
	v_lshl_add_u64 v[70:71], v[4:5], 0, v[70:71]
	v_or_b32_e32 v54, s8, v48
	global_store_dwordx4 v[70:71], v[50:53], off
	s_nop 1
	v_cvt_pk_bf16_f32 v50, v57, v55
	v_ashrrev_i32_e32 v55, 31, v54
	v_lshlrev_b64 v[54:55], 11, v[54:55]
	v_cvt_pk_bf16_f32 v51, v59, v61
	v_cvt_pk_bf16_f32 v52, v63, v65
	v_cvt_pk_bf16_f32 v53, v67, v69
	v_lshl_add_u64 v[4:5], v[4:5], 0, v[54:55]
	global_store_dwordx4 v[4:5], v[50:53], off
	s_waitcnt lgkmcnt(0)
	s_branch .LBB0_1028
